# baseline instructions plus dtype comment only; all tried edits (LDS-staged epilogue, waitcnt/prio/MFMA-order/saddr variants) measured neutral or slower and were reverted
# speedup vs baseline: 1.0061x; 1.0061x over previous
.LBB0_245:
	s_cmp_lt_u32 s46, 8
	s_cselect_b64 s[30:31], -1, 0
	s_and_b64 s[30:31], s[30:31], exec
	s_movk_i32 s30, 0xe200
	s_cselect_b32 s34, 0xfffffc00, s30
	s_mov_b32 s30, 0x1ec00000
	s_cselect_b32 s30, s30, 0x1e000000
	s_add_u32 s30, s16, s30
	s_addc_u32 s31, s17, 0
	s_add_i32 s34, s34, s5
	v_or_b32_e32 v143, s34, v150
	v_lshl_add_u64 v[152:153], v[140:141], 1, s[30:31]
	v_cvt_pk_bf16_f32 v141, v126, s0
	v_mad_i64_i32 v[144:145], s[30:31], v143, s33, v[152:153]
	v_or_b32_e32 v146, 1, v143
	global_store_short v[144:145], v141, off
	v_cvt_pk_bf16_f32 v141, v127, s0
	v_mad_i64_i32 v[146:147], s[30:31], v146, s33, v[152:153]
	v_or_b32_e32 v154, 2, v143
	global_store_short v[146:147], v141, off
	v_cvt_pk_bf16_f32 v141, v128, s0
	v_mad_i64_i32 v[154:155], s[30:31], v154, s33, v[152:153]
	v_or_b32_e32 v156, 3, v143
	global_store_short v[154:155], v141, off
	v_cvt_pk_bf16_f32 v141, v129, s0
	v_mad_i64_i32 v[156:157], s[30:31], v156, s33, v[152:153]
	global_store_short v[156:157], v141, off
	v_or_b32_e32 v141, 4, v143
	v_cvt_pk_bf16_f32 v160, v122, s0
	v_mad_i64_i32 v[158:159], s[30:31], v141, s33, v[152:153]
	global_store_short v[158:159], v160, off
	v_or_b32_e32 v160, 5, v143
	v_cvt_pk_bf16_f32 v141, v123, s0
	v_mad_i64_i32 v[160:161], s[30:31], v160, s33, v[152:153]
	v_or_b32_e32 v162, 6, v143
	global_store_short v[160:161], v141, off
	v_cvt_pk_bf16_f32 v141, v124, s0
	v_mad_i64_i32 v[162:163], s[30:31], v162, s33, v[152:153]
	v_or_b32_e32 v164, 7, v143
	global_store_short v[162:163], v141, off
	v_cvt_pk_bf16_f32 v141, v125, s0
	v_mad_i64_i32 v[164:165], s[30:31], v164, s33, v[152:153]
	global_store_short v[164:165], v141, off
	v_or_b32_e32 v141, 0x80, v143
	v_cvt_pk_bf16_f32 v168, v110, s0
	v_mad_i64_i32 v[166:167], s[30:31], v141, s33, v[152:153]
	global_store_short v[166:167], v168, off
	v_or_b32_e32 v168, 0x81, v143
	v_cvt_pk_bf16_f32 v141, v111, s0
	v_mad_i64_i32 v[168:169], s[30:31], v168, s33, v[152:153]
	v_or_b32_e32 v170, 0x82, v143
	global_store_short v[168:169], v141, off
	v_cvt_pk_bf16_f32 v141, v112, s0
	v_mad_i64_i32 v[170:171], s[30:31], v170, s33, v[152:153]
	v_or_b32_e32 v172, 0x83, v143
	global_store_short v[170:171], v141, off
	v_cvt_pk_bf16_f32 v141, v113, s0
	v_mad_i64_i32 v[172:173], s[30:31], v172, s33, v[152:153]
	global_store_short v[172:173], v141, off
	v_or_b32_e32 v141, 0x84, v143
	v_cvt_pk_bf16_f32 v176, v102, s0
	v_mad_i64_i32 v[174:175], s[30:31], v141, s33, v[152:153]
	global_store_short v[174:175], v176, off
	v_or_b32_e32 v176, 0x85, v143
	v_cvt_pk_bf16_f32 v141, v103, s0
	v_mad_i64_i32 v[176:177], s[30:31], v176, s33, v[152:153]
	v_or_b32_e32 v178, 0x86, v143
	global_store_short v[176:177], v141, off
	v_cvt_pk_bf16_f32 v141, v104, s0
	v_mad_i64_i32 v[178:179], s[30:31], v178, s33, v[152:153]
	v_or_b32_e32 v143, 0x87, v143
	global_store_short v[178:179], v141, off
	v_cvt_pk_bf16_f32 v141, v105, s0
	v_mad_i64_i32 v[152:153], s[30:31], v143, s33, v[152:153]
	global_store_short v[152:153], v141, off
	v_cvt_pk_bf16_f32 v141, v118, s0
	global_store_short v[144:145], v141, off offset:32
	v_cvt_pk_bf16_f32 v141, v119, s0
	global_store_short v[146:147], v141, off offset:32
	v_cvt_pk_bf16_f32 v141, v120, s0
	global_store_short v[154:155], v141, off offset:32
	v_cvt_pk_bf16_f32 v141, v121, s0
	global_store_short v[156:157], v141, off offset:32
	v_cvt_pk_bf16_f32 v141, v114, s0
	global_store_short v[158:159], v141, off offset:32
	v_cvt_pk_bf16_f32 v141, v115, s0
	global_store_short v[160:161], v141, off offset:32
	v_cvt_pk_bf16_f32 v141, v116, s0
	global_store_short v[162:163], v141, off offset:32
	v_cvt_pk_bf16_f32 v141, v117, s0
	global_store_short v[164:165], v141, off offset:32
	v_cvt_pk_bf16_f32 v141, v94, s0
	global_store_short v[166:167], v141, off offset:32
	v_cvt_pk_bf16_f32 v141, v95, s0
	global_store_short v[168:169], v141, off offset:32
	v_cvt_pk_bf16_f32 v141, v96, s0
	global_store_short v[170:171], v141, off offset:32
	v_cvt_pk_bf16_f32 v141, v97, s0
	global_store_short v[172:173], v141, off offset:32
	v_cvt_pk_bf16_f32 v141, v86, s0
	global_store_short v[174:175], v141, off offset:32
	v_cvt_pk_bf16_f32 v141, v87, s0
	global_store_short v[176:177], v141, off offset:32
	v_cvt_pk_bf16_f32 v141, v88, s0
	global_store_short v[178:179], v141, off offset:32
	v_cvt_pk_bf16_f32 v141, v89, s0
	global_store_short v[152:153], v141, off offset:32
	v_cvt_pk_bf16_f32 v141, v106, s0
	global_store_short v[144:145], v141, off offset:64
	v_cvt_pk_bf16_f32 v141, v107, s0
	global_store_short v[146:147], v141, off offset:64
	v_cvt_pk_bf16_f32 v141, v108, s0
	global_store_short v[154:155], v141, off offset:64
	v_cvt_pk_bf16_f32 v141, v109, s0
	global_store_short v[156:157], v141, off offset:64
	v_cvt_pk_bf16_f32 v141, v98, s0
	global_store_short v[158:159], v141, off offset:64
	v_cvt_pk_bf16_f32 v141, v99, s0
	global_store_short v[160:161], v141, off offset:64
	v_cvt_pk_bf16_f32 v141, v100, s0
	global_store_short v[162:163], v141, off offset:64
	v_cvt_pk_bf16_f32 v141, v101, s0
	global_store_short v[164:165], v141, off offset:64
	v_cvt_pk_bf16_f32 v141, v78, s0
	global_store_short v[166:167], v141, off offset:64
	v_cvt_pk_bf16_f32 v141, v79, s0
	global_store_short v[168:169], v141, off offset:64
	v_cvt_pk_bf16_f32 v141, v80, s0
	global_store_short v[170:171], v141, off offset:64
	v_cvt_pk_bf16_f32 v141, v81, s0
	global_store_short v[172:173], v141, off offset:64
	v_cvt_pk_bf16_f32 v141, v74, s0
	global_store_short v[174:175], v141, off offset:64
	v_cvt_pk_bf16_f32 v141, v75, s0
	global_store_short v[176:177], v141, off offset:64
	v_cvt_pk_bf16_f32 v141, v76, s0
	global_store_short v[178:179], v141, off offset:64
	v_cvt_pk_bf16_f32 v141, v77, s0
	global_store_short v[152:153], v141, off offset:64
	v_cvt_pk_bf16_f32 v141, v90, s0
	global_store_short v[144:145], v141, off offset:96
	v_cvt_pk_bf16_f32 v141, v91, s0
	global_store_short v[146:147], v141, off offset:96
	v_cvt_pk_bf16_f32 v141, v92, s0
	global_store_short v[154:155], v141, off offset:96
	v_cvt_pk_bf16_f32 v141, v93, s0
	global_store_short v[156:157], v141, off offset:96
	v_cvt_pk_bf16_f32 v141, v82, s0
	global_store_short v[158:159], v141, off offset:96
	v_cvt_pk_bf16_f32 v141, v83, s0
	global_store_short v[160:161], v141, off offset:96
	v_cvt_pk_bf16_f32 v141, v84, s0
	global_store_short v[162:163], v141, off offset:96
	v_cvt_pk_bf16_f32 v141, v85, s0
	global_store_short v[164:165], v141, off offset:96
	v_cvt_pk_bf16_f32 v141, v70, s0
	global_store_short v[166:167], v141, off offset:96
	v_cvt_pk_bf16_f32 v141, v71, s0
	global_store_short v[168:169], v141, off offset:96
	v_cvt_pk_bf16_f32 v141, v72, s0
	global_store_short v[170:171], v141, off offset:96
	v_cvt_pk_bf16_f32 v141, v73, s0
	global_store_short v[172:173], v141, off offset:96
	v_cvt_pk_bf16_f32 v141, v66, s0
	global_store_short v[174:175], v141, off offset:96
	v_cvt_pk_bf16_f32 v141, v67, s0
	global_store_short v[176:177], v141, off offset:96
	v_cvt_pk_bf16_f32 v141, v68, s0
	global_store_short v[178:179], v141, off offset:96
	v_cvt_pk_bf16_f32 v141, v69, s0
	global_store_short v[152:153], v141, off offset:96
	v_cvt_pk_bf16_f32 v141, v62, s0
	global_store_short v[144:145], v141, off offset:256
	v_cvt_pk_bf16_f32 v141, v63, s0
	global_store_short v[146:147], v141, off offset:256
	v_cvt_pk_bf16_f32 v141, v64, s0
	global_store_short v[154:155], v141, off offset:256
	v_cvt_pk_bf16_f32 v141, v65, s0
	global_store_short v[156:157], v141, off offset:256
	v_cvt_pk_bf16_f32 v141, v58, s0
	global_store_short v[158:159], v141, off offset:256
	v_cvt_pk_bf16_f32 v141, v59, s0
	global_store_short v[160:161], v141, off offset:256
	v_cvt_pk_bf16_f32 v141, v60, s0
	global_store_short v[162:163], v141, off offset:256
	v_cvt_pk_bf16_f32 v141, v61, s0
	global_store_short v[164:165], v141, off offset:256
	v_cvt_pk_bf16_f32 v141, v46, s0
	global_store_short v[166:167], v141, off offset:256
	v_cvt_pk_bf16_f32 v141, v47, s0
	global_store_short v[168:169], v141, off offset:256
	v_cvt_pk_bf16_f32 v141, v48, s0
	global_store_short v[170:171], v141, off offset:256
	v_cvt_pk_bf16_f32 v141, v49, s0
	global_store_short v[172:173], v141, off offset:256
	v_cvt_pk_bf16_f32 v141, v38, s0
	global_store_short v[174:175], v141, off offset:256
	v_cvt_pk_bf16_f32 v141, v39, s0
	global_store_short v[176:177], v141, off offset:256
	v_cvt_pk_bf16_f32 v141, v40, s0
	global_store_short v[178:179], v141, off offset:256
	v_cvt_pk_bf16_f32 v141, v41, s0
	global_store_short v[152:153], v141, off offset:256
	v_cvt_pk_bf16_f32 v141, v54, s0
	global_store_short v[144:145], v141, off offset:288
	v_cvt_pk_bf16_f32 v141, v55, s0
	global_store_short v[146:147], v141, off offset:288
	v_cvt_pk_bf16_f32 v141, v56, s0
	global_store_short v[154:155], v141, off offset:288
	v_cvt_pk_bf16_f32 v141, v57, s0
	global_store_short v[156:157], v141, off offset:288
	v_cvt_pk_bf16_f32 v141, v50, s0
	global_store_short v[158:159], v141, off offset:288
	v_cvt_pk_bf16_f32 v141, v51, s0
	global_store_short v[160:161], v141, off offset:288
	v_cvt_pk_bf16_f32 v141, v52, s0
	global_store_short v[162:163], v141, off offset:288
	v_cvt_pk_bf16_f32 v141, v53, s0
	global_store_short v[164:165], v141, off offset:288
	v_cvt_pk_bf16_f32 v141, v30, s0
	global_store_short v[166:167], v141, off offset:288
	v_cvt_pk_bf16_f32 v141, v31, s0
	global_store_short v[168:169], v141, off offset:288
	v_cvt_pk_bf16_f32 v141, v32, s0
	global_store_short v[170:171], v141, off offset:288
	v_cvt_pk_bf16_f32 v141, v33, s0
	global_store_short v[172:173], v141, off offset:288
	v_cvt_pk_bf16_f32 v141, v22, s0
	global_store_short v[174:175], v141, off offset:288
	v_cvt_pk_bf16_f32 v141, v23, s0
	global_store_short v[176:177], v141, off offset:288
	v_cvt_pk_bf16_f32 v141, v24, s0
	global_store_short v[178:179], v141, off offset:288
	v_cvt_pk_bf16_f32 v141, v25, s0
	global_store_short v[152:153], v141, off offset:288
	v_cvt_pk_bf16_f32 v141, v42, s0
	global_store_short v[144:145], v141, off offset:320
	v_cvt_pk_bf16_f32 v141, v43, s0
	global_store_short v[146:147], v141, off offset:320
	v_cvt_pk_bf16_f32 v141, v44, s0
	global_store_short v[154:155], v141, off offset:320
	v_cvt_pk_bf16_f32 v141, v45, s0
	global_store_short v[156:157], v141, off offset:320
	v_cvt_pk_bf16_f32 v141, v34, s0
	global_store_short v[158:159], v141, off offset:320
	v_cvt_pk_bf16_f32 v141, v35, s0
	global_store_short v[160:161], v141, off offset:320
	v_cvt_pk_bf16_f32 v141, v36, s0
	global_store_short v[162:163], v141, off offset:320
	v_cvt_pk_bf16_f32 v141, v37, s0
	global_store_short v[164:165], v141, off offset:320
	v_cvt_pk_bf16_f32 v141, v14, s0
	global_store_short v[166:167], v141, off offset:320
	v_cvt_pk_bf16_f32 v141, v15, s0
	global_store_short v[168:169], v141, off offset:320
	v_cvt_pk_bf16_f32 v141, v16, s0
	global_store_short v[170:171], v141, off offset:320
	v_cvt_pk_bf16_f32 v141, v17, s0
	global_store_short v[172:173], v141, off offset:320
	v_cvt_pk_bf16_f32 v141, v10, s0
	global_store_short v[174:175], v141, off offset:320
	v_cvt_pk_bf16_f32 v141, v11, s0
	global_store_short v[176:177], v141, off offset:320
	v_cvt_pk_bf16_f32 v141, v12, s0
	global_store_short v[178:179], v141, off offset:320
	v_cvt_pk_bf16_f32 v141, v13, s0
	global_store_short v[152:153], v141, off offset:320
	v_cvt_pk_bf16_f32 v141, v26, s0
	global_store_short v[144:145], v141, off offset:352
	v_cvt_pk_bf16_f32 v141, v27, s0
	global_store_short v[146:147], v141, off offset:352
	v_cvt_pk_bf16_f32 v141, v28, s0
	global_store_short v[154:155], v141, off offset:352
	v_cvt_pk_bf16_f32 v141, v29, s0
	global_store_short v[156:157], v141, off offset:352
	v_cvt_pk_bf16_f32 v141, v18, s0
	global_store_short v[158:159], v141, off offset:352
	v_cvt_pk_bf16_f32 v141, v19, s0
	global_store_short v[160:161], v141, off offset:352
	v_cvt_pk_bf16_f32 v141, v20, s0
	global_store_short v[162:163], v141, off offset:352
	v_cvt_pk_bf16_f32 v141, v21, s0
	global_store_short v[164:165], v141, off offset:352
	v_cvt_pk_bf16_f32 v141, v6, s0
	global_store_short v[166:167], v141, off offset:352
	v_cvt_pk_bf16_f32 v141, v7, s0
	global_store_short v[168:169], v141, off offset:352
	v_cvt_pk_bf16_f32 v141, v8, s0
	global_store_short v[170:171], v141, off offset:352
	v_cvt_pk_bf16_f32 v141, v9, s0
	global_store_short v[172:173], v141, off offset:352
	v_cvt_pk_bf16_f32 v141, v2, s0
	global_store_short v[174:175], v141, off offset:352
	v_cvt_pk_bf16_f32 v141, v3, s0
	global_store_short v[176:177], v141, off offset:352
	v_cvt_pk_bf16_f32 v141, v4, s0
	global_store_short v[178:179], v141, off offset:352
	v_cvt_pk_bf16_f32 v141, v5, s0
	global_store_short v[152:153], v141, off offset:352

	.amdhsa_kernel _Z8mega_fwd3Prm
		.amdhsa_group_segment_fixed_size 0
		.amdhsa_private_segment_fixed_size 0
		.amdhsa_kernarg_size 448
		.amdhsa_user_sgpr_count 2
		.amdhsa_user_sgpr_dispatch_ptr 0
		.amdhsa_user_sgpr_queue_ptr 0
		.amdhsa_user_sgpr_kernarg_segment_ptr 1
		.amdhsa_user_sgpr_dispatch_id 0
		.amdhsa_user_sgpr_kernarg_preload_length 0
		.amdhsa_user_sgpr_kernarg_preload_offset 0
		.amdhsa_user_sgpr_private_segment_size 0
		.amdhsa_uses_dynamic_stack 0
		.amdhsa_enable_private_segment 0
		.amdhsa_system_sgpr_workgroup_id_x 1
		.amdhsa_system_sgpr_workgroup_id_y 0
		.amdhsa_system_sgpr_workgroup_id_z 0
		.amdhsa_system_sgpr_workgroup_info 0
		.amdhsa_system_vgpr_workitem_id 2
		.amdhsa_next_free_vgpr 256
		.amdhsa_next_free_sgpr 98
		.amdhsa_accum_offset 256
		.amdhsa_reserve_vcc 1
		.amdhsa_float_round_mode_32 0
		.amdhsa_float_round_mode_16_64 0
		.amdhsa_float_denorm_mode_32 3
		.amdhsa_float_denorm_mode_16_64 3
		.amdhsa_dx10_clamp 1
		.amdhsa_ieee_mode 1
		.amdhsa_fp16_overflow 0
		.amdhsa_tg_split 0
		.amdhsa_exception_fp_ieee_invalid_op 0
		.amdhsa_exception_fp_denorm_src 0
		.amdhsa_exception_fp_ieee_div_zero 0
		.amdhsa_exception_fp_ieee_overflow 0
		.amdhsa_exception_fp_ieee_underflow 0
		.amdhsa_exception_fp_ieee_inexact 0
		.amdhsa_exception_int_div_zero 0
	.end_amdhsa_kernel

amdhsa.kernels:
  - .agpr_count:     0
    .args:
      - .offset:         0
        .size:           192
        .value_kind:     by_value
      - .offset:         192
        .size:           4
        .value_kind:     hidden_block_count_x
      - .offset:         196
        .size:           4
        .value_kind:     hidden_block_count_y
      - .offset:         200
        .size:           4
        .value_kind:     hidden_block_count_z
      - .offset:         204
        .size:           2
        .value_kind:     hidden_group_size_x
      - .offset:         206
        .size:           2
        .value_kind:     hidden_group_size_y
      - .offset:         208
        .size:           2
        .value_kind:     hidden_group_size_z
      - .offset:         210
        .size:           2
        .value_kind:     hidden_remainder_x
      - .offset:         212
        .size:           2
        .value_kind:     hidden_remainder_y
      - .offset:         214
        .size:           2
        .value_kind:     hidden_remainder_z
      - .offset:         232
        .size:           8
        .value_kind:     hidden_global_offset_x
      - .offset:         240
        .size:           8
        .value_kind:     hidden_global_offset_y
      - .offset:         248
        .size:           8
        .value_kind:     hidden_global_offset_z
      - .offset:         256
        .size:           2
        .value_kind:     hidden_grid_dims
      - .offset:         280
        .size:           8
        .value_kind:     hidden_multigrid_sync_arg
      - .offset:         312
        .size:           4
        .value_kind:     hidden_dynamic_lds_size
    .group_segment_fixed_size: 0
    .kernarg_segment_align: 8
    .kernarg_segment_size: 448
    .language:       OpenCL C
    .language_version:
      - 2
      - 0
    .max_flat_workgroup_size: 512
    .name:           _Z8mega_fwd3Prm
    .private_segment_fixed_size: 0
    .sgpr_count:     104
    .sgpr_spill_count: 243
    .symbol:         _Z8mega_fwd3Prm.kd
    .uniform_work_group_size: 1
    .uses_dynamic_stack: false
    .vgpr_count:     256
    .vgpr_spill_count: 0
    .wavefront_size: 64
